# in-proj GEMM: epilogue column info staged into LDS by in-loop LDS-DMA (wave 0, k-tile 12), conditional global loads became ds_reads; row-stat reduction behind the first store group with counted vmcnt
# speedup vs baseline: 1.0063x; 1.0019x over previous
;     __device__ __forceinline__ void prep(int pm, int par, LAS unsigned char* lds) const { if (fold) prep_rowstats(stat, pm, par, lds); }
;     __device__ __forceinline__ void prep(int pm, int par, LAS unsigned char* lds) const { if (!ident) prep_rowstats(stat, pm, par, lds); }
;     __device__ __forceinline__ void prep(int pm, int par, LAS unsigned char* lds) const { prep_rowstats(stat, pm, par, lds); }
;     __device__ __forceinline__ ColInfo colinfo(int col) const { ColInfo c; c.a = (f32x4){0.f, 0.f, 0.f, 0.f}; c.b = c.a; if (fold) { c.a = *(const f32x4*)(c1 + col); c.b = *(const f32x4*)(c2 + col); } return c; }
; template <class Epi>
; __device__ __forceinline__ void gemm_phase(LAS unsigned char* lds, const bf16_t* Ag, const bf16_t* Btg, const int K, const int nM, const int nN, const Epi& E) {
;     ...
;         for (int t = 0; t < nt; t += 2) {
;             const bool last = (t == nt - 2);
;             const char* a1 = cA + (size_t)(t + 1) * kstep;
;             const char* a2 = last ? nA : cA + (size_t)(t + 2) * kstep; const char* b2 = last ? nB : cB + (size_t)(t + 2) * kstep;
;             const char* a3 = a2 + kstep; const char* b3 = b2 + kstep;
;             if (last && has_next && pmn != pm) E.prep(pmn, par ^ 1, lds);
.LBB0_849:
	s_cmp_lg_u32 s72, 12
	s_cselect_b64 s[52:53], -1, 0
	s_cbranch_scc1 .LBB0_848
	v_cmp_gt_u32_e32 vcc, 64, v198
	s_and_saveexec_b64 s[54:55], vcc
	s_cbranch_execz .Lci0_r
	v_lshlrev_b32_e32 v130, 4, v198
	s_lshl_b32 s26, s69, 10
	v_add_u32_e32 v130, s26, v130
	v_mov_b32_e32 v131, 0
	v_lshl_add_u64 v[132:133], s[18:19], 0, v[130:131]
	v_lshl_add_u64 v[130:131], s[20:21], 0, v[130:131]
	v_readfirstlane_b32 s26, v174
	s_nop 0
	s_add_i32 m0, s26, 0x22000
	s_nop 0
	global_load_lds_dwordx4 v[132:133], off
	s_add_i32 m0, s26, 0x22400
	s_nop 0
	global_load_lds_dwordx4 v[130:131], off
.Lci0_r:
	s_or_b64 exec, exec, s[54:55]
	s_branch .LBB0_848
.LBB0_852:
	s_and_b64 vcc, exec, s[48:49]
	s_cbranch_vccnz .Lprep0_a
	v_lshrrev_b32_e32 v226, 1, v198
	v_and_b32_e32 v227, 1, v198
	v_add_u32_e32 v228, s46, v226
	v_lshlrev_b32_e32 v228, 7, v228
	v_lshl_add_u32 v228, v227, 6, v228
	v_mov_b32_e32 v229, 0
	v_lshl_add_u64 v[228:229], s[34:35], 0, v[228:229]
	global_load_dwordx4 v[232:235], v[228:229], off
	global_load_dwordx4 v[236:239], v[228:229], off offset:16
	global_load_dwordx4 v[240:243], v[228:229], off offset:32
	global_load_dwordx4 v[244:247], v[228:229], off offset:48
	v_lshl_add_u32 v226, v226, 3, v128
.Lprep0_a:
	v_lshl_add_u32 v227, v197, 2, v174
	v_add_u32_e32 v227, 0x22000, v227
	v_lshl_or_b32 v172, s69, 8, v197
	v_mov_b32_e32 v128, 0
	s_and_b64 vcc, exec, s[12:13]
	v_ashrrev_i32_e32 v173, 31, v172
	v_mov_b32_e32 v136, 0
	v_mov_b32_e32 v137, v128
	v_mov_b32_e32 v138, 0
	v_mov_b32_e32 v139, 0
	v_mov_b32_e32 v132, 0
	v_mov_b32_e32 v133, v128
	v_mov_b32_e32 v134, 0
	v_mov_b32_e32 v135, v128
	s_cbranch_vccz .LBB0_854
	ds_read_b128 v[132:135], v227 offset:1024
	ds_read_b128 v[136:139], v227
.LBB0_854:
	s_and_b64 vcc, exec, s[40:41]
	v_mov_b32_e32 v129, 0
	v_mov_b32_e32 v130, 0
	v_mov_b32_e32 v131, 0
	v_mov_b32_e32 v144, 0
	v_mov_b32_e32 v145, 0
	v_mov_b32_e32 v146, 0
	v_mov_b32_e32 v147, 0
	s_cbranch_vccnz .LBB0_856
	ds_read_b128 v[128:131], v227 offset:64
	ds_read_b128 v[144:147], v227 offset:1088
.LBB0_856:
	v_mov_b32_e32 v148, 0
	s_and_b64 vcc, exec, s[40:41]
	v_mov_b32_e32 v156, 0
	v_mov_b32_e32 v157, 0
	v_mov_b32_e32 v158, 0
	v_mov_b32_e32 v159, 0
	v_mov_b32_e32 v160, 0
	v_mov_b32_e32 v161, 0
	v_mov_b32_e32 v162, 0
	v_mov_b32_e32 v163, 0
	s_cbranch_vccnz .LBB0_858
	ds_read_b128 v[156:159], v227 offset:512
	ds_read_b128 v[160:163], v227 offset:1536
.LBB0_858:
	s_and_b64 vcc, exec, s[40:41]
	v_mov_b32_e32 v149, 0
	v_mov_b32_e32 v150, 0
	v_mov_b32_e32 v151, 0
	v_mov_b32_e32 v164, 0
	v_mov_b32_e32 v165, 0
	v_mov_b32_e32 v166, 0
	v_mov_b32_e32 v167, 0
	s_cbranch_vccnz .LBB0_860
	ds_read_b128 v[148:151], v227 offset:576
	ds_read_b128 v[164:167], v227 offset:1600

; #define LAS __attribute__((address_space(3)))
; __device__ __forceinline__ u32x2 pack4(const f32x4 a) { u32x2 v; v.x = cvt_pk_bf16(a[0], a[1]); v.y = cvt_pk_bf16(a[2], a[3]); return v; }
;     __device__ __forceinline__ f32x4 preload(int row, int col) const { const u32x2 w = *(const u32x2*)(xb + (size_t)row * DM + col); return (f32x4){bflo(w.x), bfhi(w.x), bflo(w.y), bfhi(w.y)}; }
;     __device__ __forceinline__ f32x4 preload(int row, int col) const { return (f32x4){0.f, 0.f, 0.f, 0.f}; }
;     __device__ __forceinline__ u32x2 preload_pk(int row, int col) const { return (u32x2){0u, 0u}; }
; __device__ __forceinline__ void prep_rowstats(const float* stat, int pm, int par, LAS unsigned char* lds) {
;     ...
;         for (int q = 0; q < 8; ++q) { const f32x4 v = sp[q]; s1 += v[0] + v[2]; s2 += v[1] + v[3]; }
;         const float mu = s1 * (1.0f / 1024.0f); const float var = fmaxf(s2 * (1.0f / 1024.0f) - mu * mu, 0.f);
;         ((LAS f32x2*)(lds + RS_OFF + par * 2048))[t] = (f32x2){mu, __builtin_amdgcn_rsqf(var + LN_EPS)};
;     __device__ __forceinline__ RowInfo rowinfo(int row, int lrow, int par, LAS unsigned char* lds) const {
;         RowInfo r; r.mu = 0.f; r.rstd = 1.f; if (fold) { const f32x2 sv = ((const LAS f32x2*)(lds + RS_OFF + par * 2048))[lrow]; r.mu = sv.x; r.rstd = sv.y; }
;         r.pad = 0; return r; }
;     __device__ __forceinline__ ColInfo colinfo(int col) const { ColInfo c; c.a = (f32x4){0.f, 0.f, 0.f, 0.f}; c.b = c.a; if (fold) { c.a = *(const f32x4*)(c1 + col); c.b = *(const f32x4*)(c2 + col); } return c; }
;     __device__ __forceinline__ f32x4 preload(int row, int col) const { return (f32x4){0.f, 0.f, 0.f, 0.f}; }
;     __device__ __forceinline__ u32x2 preload_pk(int row, int col) const { return (u32x2){0u, 0u}; }
;     __device__ __forceinline__ void apply(const RowInfo& ri, const ColInfo& ci, int row, int col, f32x4 a, f32x4 pv, float& s1, float& s2) const {
;         f32x4 v = a;
;         if (fold) v = (a - ci.a * ri.mu) * ri.rstd + ci.b;
;         if (ri.pad) v = (f32x4){0.f, 0.f, 0.f, 0.f};
;         *(u32x2*)(proj + (size_t)row * NPROJ + col) = pack4(v);
;     }
.LBB0_862:
	s_lshr_b32 s14, s68, 4
	s_lshl_b32 s15, s68, 8
	s_waitcnt lgkmcnt(0)
	v_xor_b32_e32 v139, 0x80000000, v139
	v_xor_b32_e32 v138, 0x80000000, v138
	v_xor_b32_e32 v217, 0x80000000, v137
	v_xor_b32_e32 v216, 0x80000000, v136
	s_mulk_i32 s14, 0x1040
	s_and_b32 s15, s15, 0xf00
	v_pk_fma_f32 v[210:211], v[138:139], v[188:189], v[154:155]
	v_pk_fma_f32 v[216:217], v[216:217], v[184:185], v[152:153]
	s_add_i32 s15, s15, s14
	v_pk_fma_f32 v[216:217], v[182:183], v[216:217], v[132:133]
	v_pk_fma_f32 v[210:211], v[186:187], v[210:211], v[134:135]
	s_or_b32 s14, s15, 48
	v_cndmask_b32_e64 v155, v211, v155, s[42:43]
	v_cndmask_b32_e64 v154, v210, v154, s[42:43]
	v_cndmask_b32_e64 v153, v217, v153, s[42:43]
	v_cndmask_b32_e64 v152, v216, v152, s[42:43]
	v_add_u32_e32 v175, s14, v176
	v_cvt_pk_bf16_f32 v152, v152, v153
	v_cvt_pk_bf16_f32 v153, v154, v155
	v_mov_b64_e32 v[154:155], s[86:87]
	v_mad_i64_i32 v[154:155], s[48:49], v175, s9, v[154:155]
	v_lshl_add_u64 v[154:155], v[172:173], 1, v[154:155]
	v_xor_b32_e32 v131, 0x80000000, v131
	v_xor_b32_e32 v130, 0x80000000, v130
	v_xor_b32_e32 v211, 0x80000000, v129
	v_xor_b32_e32 v210, 0x80000000, v128
	global_store_dwordx2 v[154:155], v[152:153], off
	v_pk_fma_f32 v[152:153], v[130:131], v[188:189], v[142:143]
	v_pk_fma_f32 v[210:211], v[210:211], v[184:185], v[140:141]
	v_pk_fma_f32 v[152:153], v[186:187], v[152:153], v[146:147]
	v_pk_fma_f32 v[210:211], v[182:183], v[210:211], v[144:145]
	v_cndmask_b32_e64 v143, v153, v143, s[42:43]
	v_cndmask_b32_e64 v142, v152, v142, s[42:43]
	v_cndmask_b32_e64 v141, v211, v141, s[42:43]
	v_cndmask_b32_e64 v140, v210, v140, s[42:43]
	v_cvt_pk_bf16_f32 v140, v140, v141
	v_cvt_pk_bf16_f32 v141, v142, v143
	global_store_dwordx2 v[154:155], v[140:141], off offset:32
	v_xor_b32_e32 v141, 0x80000000, v159
	v_xor_b32_e32 v140, 0x80000000, v158
	v_xor_b32_e32 v153, 0x80000000, v157
	v_xor_b32_e32 v152, 0x80000000, v156
	v_pk_fma_f32 v[142:143], v[140:141], v[188:189], v[126:127]
	v_pk_fma_f32 v[152:153], v[152:153], v[184:185], v[124:125]
	v_pk_fma_f32 v[142:143], v[186:187], v[142:143], v[162:163]
	v_pk_fma_f32 v[152:153], v[182:183], v[152:153], v[160:161]
	v_cndmask_b32_e64 v127, v143, v127, s[42:43]
	v_cndmask_b32_e64 v126, v142, v126, s[42:43]
	v_cndmask_b32_e64 v125, v153, v125, s[42:43]
	v_cndmask_b32_e64 v124, v152, v124, s[42:43]
	v_cvt_pk_bf16_f32 v124, v124, v125
	v_cvt_pk_bf16_f32 v125, v126, v127
	global_store_dwordx2 v[154:155], v[124:125], off offset:256
	v_xor_b32_e32 v125, 0x80000000, v151
	v_xor_b32_e32 v124, 0x80000000, v150
	v_xor_b32_e32 v143, 0x80000000, v149
	v_xor_b32_e32 v142, 0x80000000, v148
	v_pk_fma_f32 v[126:127], v[124:125], v[188:189], v[122:123]
	v_pk_fma_f32 v[142:143], v[142:143], v[184:185], v[120:121]
	v_pk_fma_f32 v[126:127], v[186:187], v[126:127], v[166:167]
	v_pk_fma_f32 v[142:143], v[182:183], v[142:143], v[164:165]
	v_cndmask_b32_e64 v123, v127, v123, s[42:43]
	v_cndmask_b32_e64 v122, v126, v122, s[42:43]
	v_cndmask_b32_e64 v121, v143, v121, s[42:43]
	v_cndmask_b32_e64 v120, v142, v120, s[42:43]
	v_cvt_pk_bf16_f32 v120, v120, v121
	v_cvt_pk_bf16_f32 v121, v122, v123
	global_store_dwordx2 v[154:155], v[120:121], off offset:288
	s_cmp_lg_u32 s48, 0
	s_cbranch_scc1 .Lprep0_b
	s_waitcnt vmcnt(4)
	v_pk_add_f32 v[248:249], v[232:233], v[234:235]
	v_pk_add_f32 v[250:251], v[236:237], v[238:239]
	v_pk_add_f32 v[248:249], v[248:249], v[250:251]
	v_pk_add_f32 v[250:251], v[240:241], v[242:243]
	v_pk_add_f32 v[248:249], v[248:249], v[250:251]
	v_pk_add_f32 v[250:251], v[244:245], v[246:247]
	v_pk_add_f32 v[248:249], v[248:249], v[250:251]
	s_nop 1
	v_mov_b32_dpp v250, v248 quad_perm:[1,0,3,2] row_mask:0xf bank_mask:0xf
	v_mov_b32_dpp v251, v249 quad_perm:[1,0,3,2] row_mask:0xf bank_mask:0xf
	s_nop 0
	v_pk_add_f32 v[248:249], v[248:249], v[250:251]
	v_pk_mul_f32 v[248:249], v[248:249], s[0:1] op_sel_hi:[1,0]
	s_nop 0
	v_fma_f32 v249, -v248, v248, v249
	v_max_f32_e32 v249, 0, v249
	v_add_f32_e32 v249, 0x3727c5ac, v249
	v_rsq_f32_e32 v249, v249
	s_nop 0
	ds_write_b64 v226, v[248:249]
.Lprep0_b:
	s_and_b64 vcc, exec, s[40:41]
	v_mov_b32_e32 v181, 0
	v_mov_b32_e32 v120, 0
	v_mov_b32_e32 v121, 0
	v_mov_b32_e32 v175, 1.0
	v_mov_b32_e32 v122, 1.0
	v_mov_b32_e32 v123, 1.0
	s_cbranch_vccnz .LBB0_864
	ds_read_b64 v[174:175], v225 offset:128
	s_waitcnt lgkmcnt(0)
	v_mov_b32_e32 v180, v174
	v_mov_b32_e32 v181, v174
	v_mov_b32_e32 v120, v174
	v_mov_b32_e32 v121, v174
	v_mov_b32_e32 v174, v175
	v_mov_b32_e32 v122, v175
	v_mov_b32_e32 v123, v175
